# GEMM: one static s_setprio 1 for waves 0-3 before the tile loop (reset after), per-segment flips removed
# baseline (speedup 1.0000x reference)
; __device__ __forceinline__ int opaque_tid() { int t = (int)threadIdx.x; asm volatile("" : "+v"(t)); return t; }
; #define PG8_STAGE(bufoff, gbase, voff) do { _Pragma("unroll") for (int _i = 0; _i < 2; ++_i) \
;         __builtin_amdgcn_global_load_lds((const unsigned*)((const char*)(gbase) + (voff)[_i]), (LAS unsigned*)(lds + (bufoff) + ldsw + _i * 8192), 16, 0, 0); } while (0)
; __device__ __forceinline__ void gemm_phase(LAS unsigned char* lds, const GemmDesc& g) {
;     const int tid = opaque_tid(), wid = __builtin_amdgcn_readfirstlane(tid >> 6), lane = tid & 63, wr = wid >> 2, wc = wid & 3, fr = lane & 15, fq = lane >> 4;
;     const int K = g.K, nt = K / BK;
;     const bool perm = (g.mode != 2);
;     unsigned voffA[2], voffB[2];
; #pragma unroll
;     for (int i = 0; i < 2; ++i) { int R, C; stage_rc(tid * 16 + i * 8192, R, C); const int Rb = perm ? ((R & ~31) + perm32(R & 31)) : R;
;         const int Ra = (g.mode == 3) ? (8 * (16 * (R >> 6) + (R & 15)) + ((R >> 4) & 3)) : R;
;         voffA[i] = (unsigned)(Ra * K + C) * 2u; voffB[i] = (unsigned)(Rb * K + C) * 2u; }
;     const size_t kstep = (size_t)(BK * 2);
;     const size_t hstep = (size_t)HALF * K * 2;
;     const size_t tstep = 2 * hstep;
;     const size_t hstepA = (g.mode == 3) ? (size_t)4 * K * 2 : hstep;
;     const unsigned ldsw = (unsigned)wid * 1024u;
;     const int aoff = lds_byte(wr * 64 + fr, fq * 8), boff = lds_byte(wc * 32 + fr, fq * 8);
;     ...
;     Unit cur, nxt; int ui = 0;
;     if (!unit_next(g, 0, cur)) return;
;     f32x4 acc[2][2][4][2];
; #pragma unroll
;     for (int a = 0; a < 2; ++a)
; #pragma unroll
;         for (int b = 0; b < 2; ++b)
; #pragma unroll
;             for (int m = 0; m < 4; ++m)
; #pragma unroll
;                 for (int n = 0; n < 2; ++n) acc[a][b][m][n] = (f32x4){0.f, 0.f, 0.f, 0.f};
;     bf16x8 At[4][2], B0[2][2], B1[2][2];
;     const char* cA = (const char*)g.A + (size_t)cur.pm * tstep; const char* cB = (const char*)g.Bt + (size_t)cur.pn * tstep;
;     PG8_STAGE(PG8_SB(0, 0), cB, voffB); PG8_STAGE(PG8_SA(0, 0), cA, voffA); PG8_STAGE(PG8_SB(0, 1), cB + hstep, voffB); PG8_STAGE(PG8_SA(0, 1), cA + hstepA, voffA);
;     if (wr == 1) PG8_BAR;
;     PG8_WAIT_V(4); PG8_BAR;
;     PG8_STAGE(PG8_SB(1, 0), cB + kstep, voffB); PG8_STAGE(PG8_SA(1, 0), cA + kstep, voffA); PG8_STAGE(PG8_SB(1, 1), cB + hstep + kstep, voffB);
;     PG8_WAIT_V(6); PG8_BAR;
.LBB0_189:
	s_and_b64 vcc, exec, s[6:7]
	s_cbranch_vccz .LBB0_388
	v_lshlrev_b32_e32 v13, 6, v9
	v_lshlrev_b32_e32 v0, 5, v0
	v_sub_u32_e32 v10, v10, v13
	v_and_b32_e32 v0, 32, v0
	v_ashrrev_i16_sdwa v10, v214, sext(v10) dst_sel:DWORD dst_unused:UNUSED_PAD src0_sel:DWORD src1_sel:BYTE_0
	v_add_u32_sdwa v10, v0, sext(v10) dst_sel:DWORD dst_unused:UNUSED_PAD src0_sel:DWORD src1_sel:WORD_0
	v_lshlrev_b32_e32 v0, 1, v8
	v_and_b32_e32 v9, 3, v9
	s_movk_i32 s8, 0xffe0
	v_and_b32_e32 v0, 24, v0
	v_and_b32_e32 v11, 4, v11
	v_and_or_b32 v8, v8, s8, v9
	v_or3_b32 v8, v8, v11, v0
	v_mul_lo_u32 v8, v8, s18
	s_ashr_i32 s7, s36, 6
	v_add_lshl_u32 v164, v8, v10, 1
	s_ashr_i32 s6, s36, 8
	s_lshl_b64 s[64:65], s[18:19], 8
	s_lshl_b64 s[66:67], s[18:19], 9
	s_lshl_b64 s[4:5], s[18:19], 3
	v_mul_i32_i24_e32 v8, 64, v5
	s_and_b64 s[22:23], exec, s[0:1]
	v_lshlrev_b32_e32 v1, 5, v1
	v_sub_u32_e32 v4, v4, v8
	s_cselect_b32 s69, s5, s65
	s_cselect_b32 s68, s4, s64
	v_and_b32_e32 v1, 32, v1
	v_ashrrev_i16_sdwa v4, v214, sext(v4) dst_sel:DWORD dst_unused:UNUSED_PAD src0_sel:DWORD src1_sel:BYTE_0
	v_and_b32_e32 v5, 3, v5
	s_ashr_i32 s5, s11, 31
	v_add_u32_sdwa v1, v1, sext(v4) dst_sel:DWORD dst_unused:UNUSED_PAD src0_sel:DWORD src1_sel:WORD_0
	v_lshlrev_b32_e32 v4, 1, v2
	v_and_or_b32 v2, v2, s8, v5
	s_mul_i32 s5, s66, s5
	s_mul_hi_u32 s8, s66, s11
	s_add_i32 s5, s8, s5
	s_lshr_b32 s8, s18, 23
	s_mul_i32 s10, s8, s11
	s_add_i32 s10, s5, s10
	s_ashr_i32 s5, s9, 31
	s_mul_i32 s5, s66, s5
	s_mul_hi_u32 s22, s66, s9
	s_add_i32 s5, s22, s5
	s_mul_i32 s8, s8, s9
	s_lshl_b32 s4, s7, 10
	v_and_b32_e32 v4, 24, v4
	v_and_b32_e32 v6, 4, v6
	s_add_i32 s5, s5, s8
	s_mul_i32 s8, s66, s9
	v_or3_b32 v2, v2, v6, v4
	s_add_u32 s40, s16, s8
	v_mul_lo_u32 v2, v2, s18
	s_addc_u32 s41, s17, s5
	s_add_i32 s5, s4, 0
	v_add_lshl_u32 v2, v2, v1, 1
	s_add_i32 m0, s5, 0x10000
	s_mul_i32 s13, s66, s11
	global_load_lds_dwordx4 v2, s[40:41]
	s_add_i32 m0, s5, 0x12000
	v_mul_lo_u32 v4, v7, s18
	s_add_u32 s42, s46, s13
	v_mul_lo_u32 v0, v12, s18
	v_add_lshl_u32 v166, v4, v1, 1
	global_load_lds_dwordx4 v164, s[40:41]
	s_addc_u32 s43, s47, s10
	s_mov_b32 m0, s5
	s_add_i32 s94, s5, 0x2000
	v_add_lshl_u32 v0, v0, v10, 1
	global_load_lds_dwordx4 v166, s[42:43]
	s_mov_b32 m0, s94
	s_add_u32 s22, s40, s64
	global_load_lds_dwordx4 v0, s[42:43]
	s_addc_u32 s23, s41, s65
	s_add_i32 m0, s5, 0x14000
	v_mov_b32_e32 v165, v3
	global_load_lds_dwordx4 v2, s[22:23]
	s_add_i32 m0, s5, 0x16000
	v_lshl_add_u64 v[12:13], s[22:23], 0, v[2:3]
	v_lshl_add_u64 v[14:15], s[22:23], 0, v[164:165]
	global_load_lds_dwordx4 v164, s[22:23]
	s_add_u32 s22, s42, s68
	s_addc_u32 s23, s43, s69
	s_add_i32 s70, s5, 0x4000
	s_mov_b32 m0, s70
	s_add_i32 s71, s5, 0x6000
	global_load_lds_dwordx4 v166, s[22:23]
	s_mov_b32 m0, s71
	v_mov_b32_e32 v167, v3
	global_load_lds_dwordx4 v0, s[22:23]
	v_mov_b32_e32 v1, v3
	v_writelane_b32 v254, s36, 54
	v_lshl_add_u64 v[4:5], s[40:41], 0, v[2:3]
	v_lshl_add_u64 v[6:7], s[40:41], 0, v[164:165]
	v_lshl_add_u64 v[8:9], s[42:43], 0, v[166:167]
	v_lshl_add_u64 v[10:11], s[42:43], 0, v[0:1]
	s_cmp_eq_u32 s6, 0
	s_cbranch_scc0 .Lgemm_noprio0
	s_setprio 1
.Lgemm_noprio0:
	s_cmp_lg_u32 s6, 1
	s_cbranch_scc1 .LBB0_192
	s_barrier

; #define PG8_WAIT_V(n) asm volatile("s_waitcnt vmcnt(" #n ")" ::: "memory")
; #define PG8_BAR __builtin_amdgcn_s_barrier()
; __device__ __forceinline__ void gemm_phase(LAS unsigned char* lds, const GemmDesc& g) {
;     ...
;     PG8_WAIT_V(0);
;     if (wr == 0) PG8_BAR;
;     PG8_BAR;
.LBB0_387:
	v_readlane_b32 s34, v254, 20
	v_readlane_b32 s35, v254, 29
	s_setprio 0
	s_barrier
